# phase 0 weight prep: nt hint on the read-once f32 weight row loads (keeps bf16 weight copies in cache), on top of v96
# speedup vs baseline: 1.0008x; 1.0008x over previous
.LBB0_512:
	v_mov_b32_e32 v25, v196
	s_lshl_b32 s18, s23, 6
	v_lshlrev_b32_e32 v26, 2, v25
	v_and_b32_e32 v15, 60, v26
	v_ashrrev_i32_e32 v14, 4, v25
	v_lshlrev_b32_e32 v0, 2, v15
	v_lshl_add_u64 v[16:17], s[6:7], 0, v[0:1]
	v_add_u32_e32 v18, s18, v14
	v_cmp_gt_i32_e64 s[4:5], s2, v15
	v_ashrrev_i32_e32 v19, 31, v18
	v_mov_b32_e32 v228, 0
	v_mov_b32_e32 v229, 0
	v_mov_b32_e32 v230, 0
	v_mov_b32_e32 v231, 0
	v_mov_b32_e32 v232, 0
	v_mov_b32_e32 v233, 0
	v_mov_b32_e32 v234, 0
	v_mov_b32_e32 v235, 0
	v_mov_b32_e32 v236, 0
	v_mov_b32_e32 v237, 0
	v_mov_b32_e32 v238, 0
	v_mov_b32_e32 v239, 0
	v_mov_b32_e32 v240, 0
	v_mov_b32_e32 v241, 0
	v_mov_b32_e32 v242, 0
	v_mov_b32_e32 v243, 0
	v_mul_lo_u32 v0, s14, v19
	v_mul_lo_u32 v4, s15, v18
	v_mad_u64_u32 v[2:3], s[20:21], s14, v18, 0
	v_add3_u32 v3, v3, v0, v4
	v_lshl_add_u64 v[248:249], v[2:3], 2, v[16:17]
	s_lshl_b64 s[26:27], s[14:15], 6
	v_lshl_add_u64 v[250:251], v[248:249], 0, s[26:27]
	v_lshl_add_u64 v[252:253], v[250:251], 0, s[26:27]
	v_lshl_add_u64 v[254:255], v[252:253], 0, s[26:27]
	s_and_saveexec_b64 s[6:7], s[4:5]
	global_load_dwordx4 v[228:231], v[248:249], off nt
	global_load_dwordx4 v[232:235], v[250:251], off nt
	global_load_dwordx4 v[236:239], v[252:253], off nt
	global_load_dwordx4 v[240:243], v[254:255], off nt
	s_or_b64 exec, exec, s[6:7]
	s_cmp_eq_u64 s[16:17], 0
	s_cbranch_scc1 .Lwp_nosc
	v_lshl_add_u64 v[2:3], v[18:19], 2, s[16:17]
	global_load_dword v244, v[2:3], off
	global_load_dword v245, v[2:3], off offset:64
	global_load_dword v246, v[2:3], off offset:128
	global_load_dword v247, v[2:3], off offset:192
	s_waitcnt vmcnt(0)
	v_mul_f32_e32 v228, v228, v244
	v_mul_f32_e32 v229, v229, v244
	v_mul_f32_e32 v230, v230, v244
	v_mul_f32_e32 v231, v231, v244
	v_mul_f32_e32 v232, v232, v245
	v_mul_f32_e32 v233, v233, v245
	v_mul_f32_e32 v234, v234, v245
	v_mul_f32_e32 v235, v235, v245
	v_mul_f32_e32 v236, v236, v246
	v_mul_f32_e32 v237, v237, v246
	v_mul_f32_e32 v238, v238, v246
	v_mul_f32_e32 v239, v239, v246
	v_mul_f32_e32 v240, v240, v247
	v_mul_f32_e32 v241, v241, v247
	v_mul_f32_e32 v242, v242, v247
	v_mul_f32_e32 v243, v243, v247
